# pipelined attention fast path with the four K/V LDS-DMA loads issued one behind each PV MFMA group
# speedup vs baseline: 1.0184x; 1.0129x over previous
; template <bool NOSHIFT> __device__ __forceinline__ void diff_attn_unit(LAS unsigned char* lds, bf16_t* proj, const bf16_t* VT, int b, int h, int qb, const AttnConsts ac, const float* gsub, const int tid, bf16_t* obuf, int opitch, int ocol) {
;     ...
;     ATT_ISSUE(0); ATT_ISSUE(1);
;     ATT_WAITBAR(4);
;     for (int t = 0; t < NT; ++t) {
;         const int bo = (t & 3) * 16384, sl_cur = bo, sl_prev = ((t - 1) & 3) * 16384;
;         if (t + 2 < NT) ATT_ISSUE(t + 2);
;         const int kv0 = 64 * t;
;         if (c == 1 && t >= 1 && kv0 - 64 <= qmax) ATT_PV(sl_prev);
;         if (kv0 <= qmax) {
;             f32x16 p[2];
;             bf16x8 kf[2][4];
; #pragma unroll
;             for (int mt = 0; mt < 2; ++mt)
; #pragma unroll
;                 for (int ks = 0; ks < 4; ++ks) kf[mt][ks] = *(const LAS bf16x8*)(lds + bo + koff[mt][ks]);
;             if constexpr (!NOSHIFT) {
; #pragma unroll
;                 for (int mt = 0; mt < 2; ++mt)
; #pragma unroll
;                     for (int r = 0; r < 16; ++r) p[mt][r] = -ac.Mfix;
;             }
;             ATT_SB;
;             __builtin_amdgcn_s_setprio(1);
; #pragma unroll
;             for (int ks = 0; ks < 4; ++ks)
; #pragma unroll
;                 for (int mt = 0; mt < 2; ++mt) {
;                     if (NOSHIFT && ks == 0) { const f32x16 z = {0.f, 0.f, 0.f, 0.f, 0.f, 0.f, 0.f, 0.f, 0.f, 0.f, 0.f, 0.f, 0.f, 0.f, 0.f, 0.f}; p[mt] = __builtin_amdgcn_mfma_f32_32x32x16_bf16(kf[mt][ks], qf[ks], z, 0, 0, 0); }
;                     else p[mt] = __builtin_amdgcn_mfma_f32_32x32x16_bf16(kf[mt][ks], qf[ks], p[mt], 0, 0, 0);
;                 }
;             __builtin_amdgcn_s_setprio(0);
;             ATT_SB;
;             const bool diag = (t >= 2 * qb);
;             if (diag) {
;                 const int qrel = qrow - kv0 - 8 * hi;
; #pragma unroll
;                 for (int mt = 0; mt < 2; ++mt)
; #pragma unroll
;                     for (int r = 0; r < 16; ++r) { float v = __builtin_amdgcn_exp2f(p[mt][r]); if (32 * mt + 16 * (r >> 3) + (r & 7) > qrel) v = 0.f; p[mt][r] = v; l += v; }
;             } else {
; #pragma unroll
;                 for (int mt = 0; mt < 2; ++mt)
; #pragma unroll
;                     for (int r = 0; r < 16; ++r) { const float v = __builtin_amdgcn_exp2f(p[mt][r]); p[mt][r] = v; l += v; }
;             }
;             asm volatile("" ::: "memory");
; #pragma unroll
.Lfp_go:
	s_addk_i32 s14, 0x4000
	s_and_b32 s15, s14, 0xc000
	v_add_u32_e32 v7, s15, v179
	v_add_u32_e32 v96, s15, v183
	v_add_u32_e32 v97, s15, v186
	v_add_u32_e32 v98, s15, v187
	ds_read_b128 v[8:11], v7
	ds_read_b128 v[12:15], v7 offset:8192
	ds_read_b128 v[128:131], v96
	ds_read_b128 v[132:135], v96 offset:8192
	ds_read_b128 v[136:139], v97
	ds_read_b128 v[140:143], v97 offset:8192
	ds_read_b128 v[144:147], v98
	ds_read_b128 v[148:151], v98 offset:8192
	s_add_i32 s80, s14, 0x8000
	s_and_b32 s80, s80, 0xc000
	v_lshl_add_u64 v[152:153], s[96:97], 0, v[4:5]
	s_mov_b64 s[16:17], 0x9e82000
	v_lshl_add_u64 v[154:155], v[152:153], 0, s[16:17]
	s_mov_b64 s[16:17], 0x9f42000
	v_lshl_add_u64 v[152:153], v[152:153], 0, s[16:17]
	v_lshl_add_u64 v[156:157], s[96:97], 0, v[2:3]
	s_mov_b64 s[16:17], 0x21a00180
	v_lshl_add_u64 v[158:159], v[156:157], 0, s[16:17]
	s_mov_b64 s[16:17], 0x21c00180
	v_lshl_add_u64 v[156:157], v[156:157], 0, s[16:17]
	s_add_i32 s81, s80, s59
	s_add_i32 s16, s80, s54
	s_setprio 1
	s_waitcnt lgkmcnt(7)
	v_mfma_f32_32x32x16_bf16 v[96:111], v[8:11], v[160:163], 0
	s_waitcnt lgkmcnt(6)
	v_mfma_f32_32x32x16_bf16 v[112:127], v[12:15], v[160:163], 0
	s_waitcnt lgkmcnt(5)
	v_mfma_f32_32x32x16_bf16 v[96:111], v[128:131], v[164:167], v[96:111]
	s_waitcnt lgkmcnt(4)
	v_mfma_f32_32x32x16_bf16 v[112:127], v[132:135], v[164:167], v[112:127]
	s_waitcnt lgkmcnt(3)
	v_mfma_f32_32x32x16_bf16 v[96:111], v[136:139], v[168:171], v[96:111]
	s_waitcnt lgkmcnt(2)
	v_mfma_f32_32x32x16_bf16 v[112:127], v[140:143], v[168:171], v[112:127]
	s_waitcnt lgkmcnt(1)
	v_mfma_f32_32x32x16_bf16 v[96:111], v[144:147], v[172:175], v[96:111]
	s_waitcnt lgkmcnt(0)
	v_mfma_f32_32x32x16_bf16 v[112:127], v[148:151], v[172:175], v[112:127]
	s_add_i32 s80, s14, 0xc000
	s_and_b32 s80, s80, 0xc000
	v_add_u32_e32 v144, s80, v193
	ds_read_b128 v[128:131], v144
	ds_read_b128 v[132:135], v144 offset:4096
	ds_read_b128 v[136:139], v144 offset:8192
	ds_read_b128 v[140:143], v144 offset:12288
	v_add_u32_e32 v145, s80, v204
	ds_read_b128 v[224:227], v145
	ds_read_b128 v[228:231], v145 offset:4096
	ds_read_b128 v[232:235], v145 offset:8192
	ds_read_b128 v[236:239], v145 offset:12288
	s_nop 1
	v_exp_f32_e32 v96, v96
	v_exp_f32_e32 v97, v97
	v_exp_f32_e32 v98, v98
	v_exp_f32_e32 v99, v99
	v_exp_f32_e32 v100, v100
	v_exp_f32_e32 v101, v101
	v_exp_f32_e32 v102, v102
	v_exp_f32_e32 v103, v103
	s_waitcnt lgkmcnt(7)
	v_mfma_f32_32x32x16_bf16 v[80:95], v[128:131], v[208:211], v[80:95]
	v_exp_f32_e32 v104, v104
	v_exp_f32_e32 v105, v105
	v_add_f32_e32 v7, v207, v96
	v_add_f32_e32 v7, v97, v7
	s_waitcnt lgkmcnt(6)
	v_mfma_f32_32x32x16_bf16 v[64:79], v[132:135], v[208:211], v[64:79]
	v_exp_f32_e32 v106, v106
	v_exp_f32_e32 v107, v107
	v_add_f32_e32 v7, v98, v7
	v_add_f32_e32 v7, v99, v7
	s_waitcnt lgkmcnt(5)
	v_mfma_f32_32x32x16_bf16 v[48:63], v[136:139], v[208:211], v[48:63]
	v_exp_f32_e32 v108, v108
	v_exp_f32_e32 v109, v109
	v_add_f32_e32 v7, v100, v7
	v_add_f32_e32 v7, v101, v7
	s_waitcnt lgkmcnt(4)
	v_mfma_f32_32x32x16_bf16 v[32:47], v[140:143], v[208:211], v[32:47]
	v_exp_f32_e32 v110, v110
	v_exp_f32_e32 v111, v111
	v_add_f32_e32 v7, v102, v7
	v_add_f32_e32 v7, v103, v7
	s_mov_b32 m0, s81
	s_nop 0
	global_load_lds_dwordx4 v[154:155], off
	v_add_u32_e32 v144, s80, v205
	ds_read_b128 v[128:131], v144
	ds_read_b128 v[132:135], v144 offset:4096
	ds_read_b128 v[136:139], v144 offset:8192
	ds_read_b128 v[140:143], v144 offset:12288
	s_waitcnt lgkmcnt(7)
	v_mfma_f32_32x32x16_bf16 v[80:95], v[224:227], v[212:215], v[80:95]
	v_cvt_pk_bf16_f32 v208, v96, v97
	v_cvt_pk_bf16_f32 v209, v98, v99
	v_exp_f32_e32 v112, v112
	v_exp_f32_e32 v113, v113
	v_add_f32_e32 v7, v104, v7
	s_waitcnt lgkmcnt(6)
	v_mfma_f32_32x32x16_bf16 v[64:79], v[228:231], v[212:215], v[64:79]
	v_cvt_pk_bf16_f32 v210, v100, v101
	v_cvt_pk_bf16_f32 v211, v102, v103
	v_exp_f32_e32 v114, v114
	v_exp_f32_e32 v115, v115
	v_add_f32_e32 v7, v105, v7
	s_waitcnt lgkmcnt(5)
	v_mfma_f32_32x32x16_bf16 v[48:63], v[232:235], v[212:215], v[48:63]
	v_exp_f32_e32 v116, v116
	v_exp_f32_e32 v117, v117
	v_add_f32_e32 v7, v106, v7
	v_add_f32_e32 v7, v107, v7
	v_add_f32_e32 v7, v108, v7
	s_waitcnt lgkmcnt(4)
	v_mfma_f32_32x32x16_bf16 v[32:47], v[236:239], v[212:215], v[32:47]
	v_exp_f32_e32 v118, v118
	v_exp_f32_e32 v119, v119
	v_add_f32_e32 v7, v109, v7
	v_add_f32_e32 v7, v110, v7
	v_add_f32_e32 v7, v111, v7
	s_add_i32 m0, s81, 0x2000
	s_nop 0
	global_load_lds_dwordx4 v[152:153], off
	v_add_u32_e32 v145, s80, v206
	ds_read_b128 v[224:227], v145
	ds_read_b128 v[228:231], v145 offset:4096
	ds_read_b128 v[232:235], v145 offset:8192
	ds_read_b128 v[236:239], v145 offset:12288
	s_waitcnt lgkmcnt(7)
	v_mfma_f32_32x32x16_bf16 v[80:95], v[128:131], v[216:219], v[80:95]
	v_cvt_pk_bf16_f32 v212, v104, v105
	v_cvt_pk_bf16_f32 v213, v106, v107
	v_exp_f32_e32 v120, v120
	v_exp_f32_e32 v121, v121
	v_add_f32_e32 v7, v112, v7
	s_waitcnt lgkmcnt(6)
	v_mfma_f32_32x32x16_bf16 v[64:79], v[132:135], v[216:219], v[64:79]
	v_cvt_pk_bf16_f32 v214, v108, v109
	v_cvt_pk_bf16_f32 v215, v110, v111
	v_exp_f32_e32 v122, v122
	v_exp_f32_e32 v123, v123
	v_add_f32_e32 v7, v113, v7
	s_waitcnt lgkmcnt(5)
	v_mfma_f32_32x32x16_bf16 v[48:63], v[136:139], v[216:219], v[48:63]
	v_exp_f32_e32 v124, v124
	v_exp_f32_e32 v125, v125
	v_add_f32_e32 v7, v114, v7
	v_add_f32_e32 v7, v115, v7
	v_add_f32_e32 v7, v116, v7
	s_waitcnt lgkmcnt(4)
	v_mfma_f32_32x32x16_bf16 v[32:47], v[140:143], v[216:219], v[32:47]
	v_exp_f32_e32 v126, v126
	v_exp_f32_e32 v127, v127
	v_add_f32_e32 v7, v117, v7
	v_add_f32_e32 v7, v118, v7
	v_add_f32_e32 v7, v119, v7
	s_mov_b32 m0, s16
	s_nop 0
	global_load_lds_dwordx4 v[158:159], off
	s_waitcnt lgkmcnt(3)
	v_mfma_f32_32x32x16_bf16 v[80:95], v[224:227], v[220:223], v[80:95]
	v_cvt_pk_bf16_f32 v216, v112, v113
	v_cvt_pk_bf16_f32 v217, v114, v115
	v_cvt_pk_bf16_f32 v218, v116, v117
	v_cvt_pk_bf16_f32 v219, v118, v119
	s_waitcnt lgkmcnt(2)
	v_mfma_f32_32x32x16_bf16 v[64:79], v[228:231], v[220:223], v[64:79]
	v_add_f32_e32 v7, v120, v7
	v_add_f32_e32 v7, v121, v7
	v_add_f32_e32 v7, v122, v7
	v_add_f32_e32 v7, v123, v7
	s_waitcnt lgkmcnt(1)
	v_mfma_f32_32x32x16_bf16 v[48:63], v[232:235], v[220:223], v[48:63]
	v_add_f32_e32 v7, v124, v7
	v_add_f32_e32 v7, v125, v7
	v_add_f32_e32 v7, v126, v7
	v_add_f32_e32 v7, v127, v7
	s_waitcnt lgkmcnt(0)
	v_mfma_f32_32x32x16_bf16 v[32:47], v[236:239], v[220:223], v[32:47]
	s_add_i32 m0, s16, 0x2000
	s_nop 0
	global_load_lds_dwordx4 v[156:157], off
	v_cvt_pk_bf16_f32 v220, v120, v121
	v_cvt_pk_bf16_f32 v221, v122, v123
	v_cvt_pk_bf16_f32 v222, v124, v125
	v_cvt_pk_bf16_f32 v223, v126, v127
	s_setprio 0
	s_branch .LBB1_298
